# v36 + FoX in-loop tiles: second key half's exp/cvt interleaved into the first half's PV MFMA shadows (in-place accumulators, same accumulation order)
# speedup vs baseline: 1.0022x; 1.0018x over previous
; __device__ __forceinline__ unsigned cvt_pk_bf16(float lo, float hi) { f32x2 v = {lo, hi}; bf16x2_t b = __builtin_convertvector(v, bf16x2_t); return __builtin_bit_cast(unsigned, b); }
; template <int TY> __device__ __forceinline__ void attn_unit(LAS unsigned char* lds, const AttnArgs& a, int b, int h, int qt, int wave_s) {
;     ...
; #pragma unroll
;         for (int qb = 0; qb < 2; ++qb) {
; #pragma unroll
;             for (int kb = 0; kb < 4; ++kb)
; #pragma unroll
;                 for (int r = 0; r < 4; ++r) s[qb][kb][r] = __builtin_amdgcn_exp2f(s[qb][kb][r]);
; #pragma unroll
;             for (int G = 0; G < 2; ++G) {
;                 u32x4 w; w.x = cvt_pk_bf16(s[qb][2 * G][0], s[qb][2 * G][1]); w.y = cvt_pk_bf16(s[qb][2 * G][2], s[qb][2 * G][3]);
;                 w.z = cvt_pk_bf16(s[qb][2 * G + 1][0], s[qb][2 * G + 1][1]); w.w = cvt_pk_bf16(s[qb][2 * G + 1][2], s[qb][2 * G + 1][3]);
;                 pf[qb][G] = __builtin_bit_cast(bf16x8, w);
;             }
;         }
; #pragma unroll
;         for (int G = 0; G < 2; ++G) {
;             lacc[0] = __builtin_amdgcn_mfma_f32_16x16x32_bf16(ones, pf[0][G], lacc[0], 0, 0, 0);
;             lacc[1] = __builtin_amdgcn_mfma_f32_16x16x32_bf16(ones, pf[1][G], lacc[1], 0, 0, 0);
;         }
; #pragma unroll
;         for (int db = 0; db < 4; ++db)
; #pragma unroll
;             for (int G = 0; G < 2; ++G) {
;                 o[0][db] = __builtin_amdgcn_mfma_f32_16x16x32_bf16(vf[db][G], pf[0][G], o[0][db], 0, 0, 0);
;                 o[1][db] = __builtin_amdgcn_mfma_f32_16x16x32_bf16(vf[db][G], pf[1][G], o[1][db], 0, 0, 0);
;             }
.LBB0_771:
	v_exp_f32_e32 v114, v114
	v_exp_f32_e32 v115, v115
	v_exp_f32_e32 v116, v116
	v_exp_f32_e32 v117, v117
	v_exp_f32_e32 v126, v126
	v_exp_f32_e32 v127, v127
	v_exp_f32_e32 v128, v128
	v_exp_f32_e32 v129, v129
	v_cvt_pk_bf16_f32 v114, v114, v115
	v_exp_f32_e32 v18, v18
	v_exp_f32_e32 v1, v1
	v_exp_f32_e32 v20, v20
	v_exp_f32_e32 v21, v21
	v_exp_f32_e32 v115, v118
	v_exp_f32_e32 v142, v119
	v_exp_f32_e32 v143, v120
	v_exp_f32_e32 v121, v121
	v_cvt_pk_bf16_f32 v118, v18, v1
	v_cvt_pk_bf16_f32 v119, v20, v21
	v_cvt_pk_bf16_f32 v120, v115, v142
	v_cvt_pk_bf16_f32 v121, v143, v121
	v_cvt_pk_bf16_f32 v115, v116, v117
	v_cvt_pk_bf16_f32 v116, v126, v127
	v_cvt_pk_bf16_f32 v117, v128, v129
	v_mfma_f32_16x16x32_bf16 v[30:33], v[10:13], v[118:121], v[30:33]
	v_exp_f32_e32 v122, v122
	v_mfma_f32_16x16x32_bf16 v[82:85], v[10:13], v[114:117], v[82:85]
	v_exp_f32_e32 v123, v123
	v_mfma_f32_16x16x32_bf16 v[26:29], v[102:105], v[118:121], v[26:29]
	v_exp_f32_e32 v124, v124
	v_mfma_f32_16x16x32_bf16 v[78:81], v[102:105], v[114:117], v[78:81]
	v_exp_f32_e32 v125, v125
	v_mfma_f32_16x16x32_bf16 v[6:9], v[54:57], v[118:121], v[6:9]
	v_exp_f32_e32 v136, v136
	v_mfma_f32_16x16x32_bf16 v[34:37], v[94:97], v[118:121], v[34:37]
	v_exp_f32_e32 v137, v137
	v_mfma_f32_16x16x32_bf16 v[86:89], v[94:97], v[114:117], v[86:89]
	v_exp_f32_e32 v138, v138
	v_mfma_f32_16x16x32_bf16 v[22:25], v[106:109], v[118:121], v[22:25]
	v_exp_f32_e32 v139, v139
	v_mfma_f32_16x16x32_bf16 v[58:61], v[106:109], v[114:117], v[58:61]
	v_cvt_pk_bf16_f32 v122, v122, v123
	v_cvt_pk_bf16_f32 v123, v124, v125
	v_mfma_f32_16x16x32_bf16 v[2:5], v[54:57], v[114:117], v[2:5]
	v_cvt_pk_bf16_f32 v124, v136, v137
	v_cvt_pk_bf16_f32 v125, v138, v139
	v_exp_f32_e32 v130, v130
	v_exp_f32_e32 v131, v131
	v_mfma_f32_16x16x32_bf16 v[30:33], v[14:17], v[122:125], v[30:33]
	v_exp_f32_e32 v132, v132
	v_mfma_f32_16x16x32_bf16 v[26:29], v[98:101], v[122:125], v[26:29]
	v_exp_f32_e32 v133, v133
	v_mfma_f32_16x16x32_bf16 v[6:9], v[54:57], v[122:125], v[6:9]
	v_exp_f32_e32 v140, v140
	v_mfma_f32_16x16x32_bf16 v[34:37], v[90:93], v[122:125], v[34:37]
	v_exp_f32_e32 v141, v141
	v_mfma_f32_16x16x32_bf16 v[22:25], v[110:113], v[122:125], v[22:25]
	v_exp_f32_e32 v1, v134
	v_exp_f32_e32 v18, v135
	v_cvt_pk_bf16_f32 v126, v130, v131
	v_cvt_pk_bf16_f32 v127, v132, v133
	v_cvt_pk_bf16_f32 v128, v140, v141
	v_cvt_pk_bf16_f32 v129, v1, v18
	s_nop 1
	v_mfma_f32_16x16x32_bf16 v[82:85], v[14:17], v[126:129], v[82:85]
	v_mfma_f32_16x16x32_bf16 v[78:81], v[98:101], v[126:129], v[78:81]
	v_mfma_f32_16x16x32_bf16 v[86:89], v[90:93], v[126:129], v[86:89]
	v_mfma_f32_16x16x32_bf16 v[58:61], v[110:113], v[126:129], v[58:61]
	v_mfma_f32_16x16x32_bf16 v[2:5], v[54:57], v[126:129], v[2:5]
	s_bitcmp1_b32 s41, 8
	s_cbranch_scc0 .LBB0_777
